# GEMM phases: per-phase s_setprio flips removed from the K-loops; one static s_setprio 1 for waves 4-7 per GEMM phase (reset after the phase)
# baseline (speedup 1.0000x reference)
.LBB0_246:
	s_ashr_i32 s52, s46, 31
	s_ashr_i32 s58, s47, 31
	s_add_u32 s0, s96, 0x8b00000
	s_addc_u32 s1, s97, 0
	s_add_u32 s88, s96, 0x31238800
	s_addc_u32 s89, s97, 0
	s_add_u32 s4, s96, 0x34238800
	s_addc_u32 s5, s97, 0
	v_writelane_b32 v252, s4, 56
	s_add_u32 s74, s96, 0x35238800
	s_addc_u32 s75, s97, 0
	v_writelane_b32 v252, s5, 57
	s_andn2_b64 vcc, exec, s[2:3]
	v_writelane_b32 v252, s56, 58
	s_nop 1
	v_writelane_b32 v252, s57, 59
	s_cbranch_vccnz .LBB0_625
	s_waitcnt vmcnt(2)
	v_ashrrev_i32_e32 v1, 31, v8
	v_lshrrev_b32_e32 v1, 26, v1
	v_add_u32_e32 v1, v8, v1
	v_ashrrev_i32_e32 v9, 6, v1
	v_bfe_i32 v1, v8, 27, 1
	v_lshlrev_b32_e32 v0, 4, v8
	v_lshrrev_b32_e32 v1, 22, v1
	v_add_u32_e32 v1, v0, v1
	v_and_b32_e32 v1, 0xfffffc00, v1
	v_sub_u32_e32 v1, v0, v1
	v_lshrrev_b32_e32 v2, 4, v1
	v_bitop3_b32 v2, v2, v1, 32 bitop3:0x6c
	v_ashrrev_i32_e32 v1, 31, v1
	v_lshrrev_b32_e32 v1, 26, v1
	v_add_u32_e32 v1, v2, v1
	v_ashrrev_i32_e32 v10, 6, v1
	v_lshlrev_b32_e32 v3, 3, v9
	s_waitcnt vmcnt(0)
	v_mul_i32_i24_e32 v4, 64, v10
	v_and_b32_e32 v3, -16, v3
	v_sub_u32_e32 v2, v2, v4
	v_mov_b32_e32 v4, 1
	v_add_u32_e32 v1, v10, v3
	v_lshlrev_b32_e32 v3, 5, v9
	v_ashrrev_i16_sdwa v2, v4, sext(v2) dst_sel:DWORD dst_unused:UNUSED_PAD src0_sel:DWORD src1_sel:BYTE_0
	v_and_b32_e32 v3, 32, v3
	v_bfe_i32 v11, v2, 0, 16
	v_and_b32_e32 v6, 3, v10
	s_mov_b32 s3, 0xfffe0
	v_add_lshl_u32 v3, v3, v11, 1
	v_add_u32_e32 v0, 0x2000, v0
	v_lshlrev_b32_e32 v2, 1, v1
	v_lshrrev_b32_e32 v5, 2, v1
	v_and_or_b32 v6, v1, s3, v6
	v_lshl_add_u32 v148, v1, 12, v3
	v_ashrrev_i32_e32 v1, 31, v0
	v_lshrrev_b32_e32 v1, 22, v1
	v_add_u32_e32 v1, v0, v1
	v_ashrrev_i32_e32 v12, 10, v1
	v_mul_i32_i24_e32 v1, 0x400, v12
	v_sub_u32_e32 v0, v0, v1
	v_and_b32_e32 v2, 24, v2
	v_and_b32_e32 v5, 4, v5
	v_lshrrev_b32_e32 v1, 4, v0
	v_or3_b32 v2, v6, v5, v2
	v_bitop3_b32 v0, v1, v0, 32 bitop3:0x6c
	v_lshl_add_u32 v150, v2, 12, v3
	v_ashrrev_i32_e32 v2, 31, v0
	v_lshrrev_b32_e32 v2, 26, v2
	v_add_u32_e32 v2, v0, v2
	v_lshlrev_b32_e32 v1, 3, v12
	v_ashrrev_i32_e32 v13, 6, v2
	v_and_b32_e32 v2, 0xc0, v2
	v_and_b32_e32 v1, -16, v1
	v_sub_u32_e32 v0, v0, v2
	s_ashr_i32 s2, s31, 6
	v_add_u32_e32 v1, v13, v1
	v_ashrrev_i16_sdwa v0, v4, sext(v0) dst_sel:DWORD dst_unused:UNUSED_PAD src0_sel:DWORD src1_sel:BYTE_0
	v_and_b32_e32 v4, 3, v13
	s_ashr_i32 s91, s90, 31
	s_ashr_i32 s83, s82, 31
	v_and_or_b32 v4, v1, s3, v4
	s_ashr_i32 s3, s31, 8
	s_lshl_b32 s33, s2, 10
	s_lshl_b64 s[4:5], s[90:91], 20
	s_lshl_b64 s[6:7], s[82:83], 20
	s_add_u32 s6, s56, s6
	v_lshlrev_b32_e32 v3, 5, v12
	v_bfe_i32 v14, v0, 0, 16
	v_lshlrev_b32_e32 v0, 1, v1
	v_lshrrev_b32_e32 v2, 2, v1
	s_addc_u32 s7, s57, s7
	s_add_i32 s44, s33, 0
	v_and_b32_e32 v3, 32, v3
	v_and_b32_e32 v0, 24, v0
	v_and_b32_e32 v2, 4, v2
	s_add_i32 m0, s44, 0x10000
	v_or3_b32 v0, v4, v2, v0
	v_add_lshl_u32 v2, v3, v14, 1
	global_load_lds_dwordx4 v150, s[6:7]
	s_add_i32 m0, s44, 0x12000
	v_lshl_add_u32 v154, v0, 12, v2
	s_add_u32 s4, s96, s4
	global_load_lds_dwordx4 v154, s[6:7]
	s_addc_u32 s5, s97, s5
	s_mov_b32 m0, s44
	s_add_i32 s45, s44, 0x2000
	v_lshl_add_u32 v152, v1, 12, v2
	global_load_lds_dwordx4 v148, s[4:5]
	s_mov_b32 m0, s45
	s_add_u32 s8, s6, 0x80000
	global_load_lds_dwordx4 v152, s[4:5]
	s_addc_u32 s9, s7, 0
	s_add_i32 m0, s44, 0x14000
	v_mov_b32_e32 v157, 0
	global_load_lds_dwordx4 v150, s[8:9]
	s_add_i32 m0, s44, 0x16000
	v_mov_b32_e32 v151, v157
	global_load_lds_dwordx4 v154, s[8:9]
	s_add_u32 s8, s4, 0x80000
	s_addc_u32 s9, s5, 0
	s_add_i32 s51, s44, 0x4000
	s_mov_b32 m0, s51
	s_add_i32 s55, s44, 0x6000
	global_load_lds_dwordx4 v148, s[8:9]
	s_mov_b32 m0, s55
	v_mov_b32_e32 v155, v157
	global_load_lds_dwordx4 v152, s[8:9]
	v_mov_b32_e32 v149, v157
	v_mov_b32_e32 v153, v157
	s_movk_i32 s56, 0x2000
	s_mov_b32 s21, 0
	v_lshl_add_u64 v[6:7], s[6:7], 0, v[150:151]
	v_lshl_add_u64 v[4:5], s[6:7], 0, v[154:155]
	v_lshl_add_u64 v[2:3], s[4:5], 0, v[148:149]
	s_cmp_lg_u32 s3, 1
	v_lshl_add_u64 v[0:1], s[4:5], 0, v[152:153]
	s_cbranch_scc1 .LBB0_249
	s_barrier
	s_setprio 1

.LBB0_624:
	s_barrier
	s_setprio 0

.LBB0_960:
	v_ashrrev_i32_e32 v1, 31, v8
	v_lshrrev_b32_e32 v1, 26, v1
	v_add_u32_e32 v1, v8, v1
	v_ashrrev_i32_e32 v9, 6, v1
	v_bfe_i32 v1, v8, 27, 1
	v_lshlrev_b32_e32 v0, 4, v8
	v_lshrrev_b32_e32 v1, 22, v1
	v_add_u32_e32 v1, v0, v1
	v_and_b32_e32 v1, 0xfffffc00, v1
	v_sub_u32_e32 v1, v0, v1
	v_lshrrev_b32_e32 v2, 4, v1
	v_bitop3_b32 v2, v2, v1, 32 bitop3:0x6c
	v_ashrrev_i32_e32 v1, 31, v1
	v_lshrrev_b32_e32 v1, 26, v1
	v_lshlrev_b32_e32 v3, 3, v9
	v_add_u32_e32 v1, v2, v1
	v_and_b32_e32 v3, -16, v3
	v_ashrrev_i32_e32 v11, 6, v1
	v_add_u32_e32 v1, v11, v3
	v_lshlrev_b32_e32 v3, 5, v9
	v_and_b32_e32 v10, 32, v3
	v_mul_i32_i24_e32 v3, 64, v11
	v_sub_u32_e32 v2, v2, v3
	v_mov_b32_e32 v3, 1
	s_ashr_i32 s4, s3, 3
	v_ashrrev_i16_sdwa v2, v3, sext(v2) dst_sel:DWORD dst_unused:UNUSED_PAD src0_sel:DWORD src1_sel:BYTE_0
	v_lshlrev_b32_e32 v4, 1, v1
	v_lshrrev_b32_e32 v5, 2, v1
	v_and_b32_e32 v6, 3, v11
	s_mov_b32 s3, 0x7fffe0
	v_bfe_i32 v12, v2, 0, 16
	v_and_b32_e32 v4, 24, v4
	v_and_b32_e32 v5, 4, v5
	v_and_or_b32 v6, v1, s3, v6
	s_movk_i32 s0, 0xe00
	v_add_u32_e32 v2, v10, v12
	v_or3_b32 v4, v6, v5, v4
	v_mul_lo_u32 v1, v1, s0
	s_waitcnt vmcnt(18)
	v_add_lshl_u32 v128, v2, v1, 1
	v_mul_u32_u24_e32 v1, 0xe00, v4
	v_add_u32_e32 v0, 0x2000, v0
	v_add_lshl_u32 v130, v1, v2, 1
	v_ashrrev_i32_e32 v1, 31, v0
	v_lshrrev_b32_e32 v1, 22, v1
	v_add_u32_e32 v1, v0, v1
	s_add_i32 s2, s2, s4
	v_ashrrev_i32_e32 v13, 10, v1
	s_ashr_i32 s4, s2, 31
	v_mul_i32_i24_e32 v1, 0x400, v13
	s_lshr_b32 s4, s4, 26
	v_sub_u32_e32 v0, v0, v1
	s_add_i32 s4, s2, s4
	v_lshrrev_b32_e32 v1, 4, v0
	s_ashr_i32 s5, s4, 6
	s_andn2_b32 s4, s4, 63
	v_bitop3_b32 v0, v1, v0, 32 bitop3:0x6c
	s_sub_i32 s4, s2, s4
	v_ashrrev_i32_e32 v2, 31, v0
	s_bfe_i32 s2, s4, 0x80000
	v_lshrrev_b32_e32 v2, 26, v2
	s_bfe_u32 s2, s2, 0x3000c
	v_lshlrev_b32_e32 v1, 3, v13
	v_add_u32_e32 v2, v0, v2
	s_add_i32 s8, s4, s2
	v_and_b32_e32 v1, -16, v1
	v_ashrrev_i32_e32 v14, 6, v2
	v_lshlrev_b32_e32 v4, 5, v13
	s_bfe_i32 s2, s8, 0x80000
	s_and_b32 s8, s8, 0xf8
	v_add_u32_e32 v1, v14, v1
	v_and_b32_e32 v15, 32, v4
	v_and_b32_e32 v4, 3, v14
	s_sext_i32_i16 s9, s2
	s_sub_i32 s4, s4, s8
	v_and_b32_e32 v2, 0xc0, v2
	v_and_or_b32 v4, v1, s3, v4
	s_ashr_i32 s3, s22, 6
	s_lshl_b32 s5, s5, 3
	s_sext_i32_i8 s4, s4
	s_ashr_i32 s8, s9, 3
	s_ashr_i32 s1, s22, 8
	v_sub_u32_e32 v0, v0, v2
	s_lshl_b32 s23, s3, 10
	s_lshr_b32 s2, s9, 3
	s_add_i32 s34, s5, s4
	s_mul_hi_i32 s9, s8, 0x1c0000
	s_mul_i32 s8, s8, 0x1c0000
	v_ashrrev_i16_sdwa v0, v3, sext(v0) dst_sel:DWORD dst_unused:UNUSED_PAD src0_sel:DWORD src1_sel:BYTE_0
	v_lshlrev_b32_e32 v2, 1, v1
	v_lshrrev_b32_e32 v3, 2, v1
	s_add_u32 s16, s68, s8
	v_bfe_i32 v16, v0, 0, 16
	v_and_b32_e32 v2, 24, v2
	v_and_b32_e32 v3, 4, v3
	s_addc_u32 s17, s69, s9
	s_add_i32 s24, s23, 0
	v_add_u32_e32 v0, v15, v16
	v_or3_b32 v2, v4, v3, v2
	v_mul_lo_u32 v1, v1, s0
	s_add_i32 m0, s24, 0x10000
	v_add_lshl_u32 v132, v0, v1, 1
	v_mul_u32_u24_e32 v1, 0xe00, v2
	s_mul_i32 s5, s34, 0x1c0000
	global_load_lds_dwordx4 v130, s[16:17]
	s_add_i32 m0, s24, 0x12000
	v_add_lshl_u32 v134, v1, v0, 1
	s_mul_hi_i32 s4, s34, 0x1c0000
	s_add_u32 s14, s92, s5
	global_load_lds_dwordx4 v134, s[16:17]
	s_addc_u32 s15, s93, s4
	s_mov_b32 m0, s24
	s_add_i32 s25, s24, 0x2000
	global_load_lds_dwordx4 v128, s[14:15]
	s_mov_b32 m0, s25
	s_add_u32 s4, s16, 0xe0000
	global_load_lds_dwordx4 v132, s[14:15]
	s_addc_u32 s5, s17, 0
	s_add_i32 m0, s24, 0x14000
	v_mov_b32_e32 v131, 0
	global_load_lds_dwordx4 v130, s[4:5]
	s_add_i32 m0, s24, 0x16000
	v_mov_b32_e32 v135, v131
	global_load_lds_dwordx4 v134, s[4:5]
	s_add_u32 s4, s14, 0xe0000
	s_addc_u32 s5, s15, 0
	s_add_i32 s26, s24, 0x4000
	s_mov_b32 m0, s26
	s_add_i32 s27, s24, 0x6000
	global_load_lds_dwordx4 v128, s[4:5]
	s_mov_b32 m0, s27
	v_mov_b32_e32 v129, v131
	global_load_lds_dwordx4 v132, s[4:5]
	v_mov_b32_e32 v133, v131
	s_mov_b32 s28, 0
	v_lshl_add_u64 v[6:7], s[16:17], 0, v[130:131]
	v_lshl_add_u64 v[4:5], s[16:17], 0, v[134:135]
	v_lshl_add_u64 v[2:3], s[14:15], 0, v[128:129]
	s_cmp_lg_u32 s1, 1
	v_lshl_add_u64 v[0:1], s[14:15], 0, v[132:133]
	s_cbranch_scc1 .LBB0_962
	s_barrier
	s_setprio 1

.LBB0_1188:
	s_add_u32 s14, s96, 0x26fc0000
	s_addc_u32 s15, s97, 0
	s_andn2_b64 vcc, exec, s[2:3]
	s_cbranch_vccnz .LBB0_1236
	v_ashrrev_i32_e32 v1, 31, v8
	v_lshrrev_b32_e32 v1, 26, v1
	v_add_u32_e32 v1, v8, v1
	v_ashrrev_i32_e32 v9, 6, v1
	v_bfe_i32 v1, v8, 27, 1
	v_lshlrev_b32_e32 v0, 4, v8
	v_lshrrev_b32_e32 v1, 22, v1
	v_add_u32_e32 v1, v0, v1
	v_and_b32_e32 v1, 0xfffffc00, v1
	v_sub_u32_e32 v1, v0, v1
	v_lshrrev_b32_e32 v2, 4, v1
	v_bitop3_b32 v2, v2, v1, 32 bitop3:0x6c
	v_ashrrev_i32_e32 v1, 31, v1
	v_lshrrev_b32_e32 v1, 26, v1
	v_add_u32_e32 v1, v2, v1
	v_ashrrev_i32_e32 v10, 6, v1
	v_lshlrev_b32_e32 v3, 3, v9
	v_mul_i32_i24_e32 v4, 64, v10
	v_and_b32_e32 v3, -16, v3
	v_sub_u32_e32 v2, v2, v4
	v_mov_b32_e32 v4, 1
	v_add_u32_e32 v1, v10, v3
	v_lshlrev_b32_e32 v3, 5, v9
	v_ashrrev_i16_sdwa v2, v4, sext(v2) dst_sel:DWORD dst_unused:UNUSED_PAD src0_sel:DWORD src1_sel:BYTE_0
	v_and_b32_e32 v3, 32, v3
	v_bfe_i32 v11, v2, 0, 16
	v_and_b32_e32 v6, 3, v10
	s_mov_b32 s3, 0xfffe0
	v_add_lshl_u32 v3, v3, v11, 1
	v_add_u32_e32 v0, 0x2000, v0
	v_lshlrev_b32_e32 v2, 1, v1
	v_lshrrev_b32_e32 v5, 2, v1
	v_and_or_b32 v6, v1, s3, v6
	v_lshl_add_u32 v128, v1, 12, v3
	v_ashrrev_i32_e32 v1, 31, v0
	v_lshrrev_b32_e32 v1, 22, v1
	v_add_u32_e32 v1, v0, v1
	v_ashrrev_i32_e32 v12, 10, v1
	v_mul_i32_i24_e32 v1, 0x400, v12
	v_sub_u32_e32 v0, v0, v1
	v_and_b32_e32 v2, 24, v2
	v_and_b32_e32 v5, 4, v5
	v_lshrrev_b32_e32 v1, 4, v0
	v_or3_b32 v2, v6, v5, v2
	v_bitop3_b32 v0, v1, v0, 32 bitop3:0x6c
	v_lshl_add_u32 v130, v2, 12, v3
	v_ashrrev_i32_e32 v2, 31, v0
	v_lshrrev_b32_e32 v2, 26, v2
	v_add_u32_e32 v2, v0, v2
	v_lshlrev_b32_e32 v1, 3, v12
	v_ashrrev_i32_e32 v13, 6, v2
	v_and_b32_e32 v2, 0xc0, v2
	v_and_b32_e32 v1, -16, v1
	v_sub_u32_e32 v0, v0, v2
	v_add_u32_e32 v1, v13, v1
	v_ashrrev_i16_sdwa v0, v4, sext(v0) dst_sel:DWORD dst_unused:UNUSED_PAD src0_sel:DWORD src1_sel:BYTE_0
	v_and_b32_e32 v4, 3, v13
	v_and_or_b32 v4, v1, s3, v4
	s_ashr_i32 s3, s19, 6
	s_ashr_i32 s2, s19, 8
	s_lshl_b32 s33, s3, 10
	s_add_u32 s36, s96, 0x24ec0000
	s_addc_u32 s37, s97, 0
	s_ashr_i32 s17, s16, 31
	s_ashr_i32 s7, s6, 31
	s_lshl_b64 s[4:5], s[16:17], 20
	s_lshl_b64 s[8:9], s[6:7], 20
	s_add_u32 s30, s66, s8
	v_lshlrev_b32_e32 v3, 5, v12
	v_bfe_i32 v14, v0, 0, 16
	v_lshlrev_b32_e32 v0, 1, v1
	v_lshrrev_b32_e32 v2, 2, v1
	s_addc_u32 s31, s67, s9
	s_add_i32 s17, s33, 0
	v_and_b32_e32 v3, 32, v3
	v_and_b32_e32 v0, 24, v0
	v_and_b32_e32 v2, 4, v2
	s_add_i32 m0, s17, 0x10000
	v_or3_b32 v0, v4, v2, v0
	v_add_lshl_u32 v2, v3, v14, 1
	global_load_lds_dwordx4 v130, s[30:31]
	s_add_i32 m0, s17, 0x12000
	v_lshl_add_u32 v134, v0, 12, v2
	s_add_u32 s28, s36, s4
	global_load_lds_dwordx4 v134, s[30:31]
	s_addc_u32 s29, s37, s5
	s_mov_b32 m0, s17
	s_add_i32 s38, s17, 0x2000
	v_lshl_add_u32 v132, v1, 12, v2
	global_load_lds_dwordx4 v128, s[28:29]
	s_mov_b32 m0, s38
	s_add_u32 s4, s30, 0x80000
	global_load_lds_dwordx4 v132, s[28:29]
	s_addc_u32 s5, s31, 0
	s_add_i32 m0, s17, 0x14000
	v_mov_b32_e32 v131, 0
	global_load_lds_dwordx4 v130, s[4:5]
	s_add_i32 m0, s17, 0x16000
	v_mov_b32_e32 v135, v131
	global_load_lds_dwordx4 v134, s[4:5]
	s_add_u32 s4, s28, 0x80000
	s_addc_u32 s5, s29, 0
	s_add_i32 s39, s17, 0x4000
	s_mov_b32 m0, s39
	s_add_i32 s40, s17, 0x6000
	global_load_lds_dwordx4 v128, s[4:5]
	s_mov_b32 m0, s40
	v_mov_b32_e32 v129, v131
	global_load_lds_dwordx4 v132, s[4:5]
	v_mov_b32_e32 v133, v131
	s_mov_b32 s5, 0
	v_lshl_add_u64 v[6:7], s[30:31], 0, v[130:131]
	v_lshl_add_u64 v[4:5], s[30:31], 0, v[134:135]
	v_lshl_add_u64 v[2:3], s[28:29], 0, v[128:129]
	s_cmp_lg_u32 s2, 1
	v_lshl_add_u64 v[0:1], s[28:29], 0, v[132:133]
	s_cbranch_scc1 .LBB0_1191
	s_barrier
	s_setprio 1

.LBB0_1388:
	v_ashrrev_i32_e32 v1, 31, v8
	v_lshrrev_b32_e32 v1, 26, v1
	v_add_u32_e32 v1, v8, v1
	v_ashrrev_i32_e32 v9, 6, v1
	v_bfe_i32 v1, v8, 27, 1
	v_lshlrev_b32_e32 v0, 4, v8
	v_lshrrev_b32_e32 v1, 22, v1
	v_add_u32_e32 v1, v0, v1
	v_and_b32_e32 v1, 0xfffffc00, v1
	v_sub_u32_e32 v1, v0, v1
	v_lshrrev_b32_e32 v2, 4, v1
	v_bitop3_b32 v2, v2, v1, 32 bitop3:0x6c
	v_ashrrev_i32_e32 v1, 31, v1
	v_lshrrev_b32_e32 v1, 26, v1
	v_lshlrev_b32_e32 v3, 3, v9
	v_add_u32_e32 v1, v2, v1
	v_and_b32_e32 v3, -16, v3
	v_ashrrev_i32_e32 v10, 6, v1
	v_add_u32_e32 v1, v10, v3
	v_lshlrev_b32_e32 v3, 5, v9
	v_and_b32_e32 v11, 32, v3
	v_mul_i32_i24_e32 v3, 64, v10
	v_sub_u32_e32 v2, v2, v3
	v_mov_b32_e32 v3, 1
	v_ashrrev_i16_sdwa v2, v3, sext(v2) dst_sel:DWORD dst_unused:UNUSED_PAD src0_sel:DWORD src1_sel:BYTE_0
	v_lshlrev_b32_e32 v4, 1, v1
	v_lshrrev_b32_e32 v5, 2, v1
	v_and_b32_e32 v6, 3, v10
	s_mov_b32 s5, 0x7fffe0
	v_bfe_i32 v12, v2, 0, 16
	v_and_b32_e32 v4, 24, v4
	v_and_b32_e32 v5, 4, v5
	v_and_or_b32 v6, v1, s5, v6
	s_movk_i32 s2, 0xa00
	v_add_u32_e32 v2, v11, v12
	v_or3_b32 v4, v6, v5, v4
	v_mul_lo_u32 v1, v1, s2
	v_add_lshl_u32 v128, v2, v1, 1
	v_mul_u32_u24_e32 v1, 0xa00, v4
	v_add_u32_e32 v0, 0x2000, v0
	v_add_lshl_u32 v130, v1, v2, 1
	v_ashrrev_i32_e32 v1, 31, v0
	v_lshrrev_b32_e32 v1, 22, v1
	v_add_u32_e32 v1, v0, v1
	s_add_i32 s4, s4, s6
	v_ashrrev_i32_e32 v13, 10, v1
	s_ashr_i32 s6, s4, 31
	v_mul_i32_i24_e32 v1, 0x400, v13
	s_lshr_b32 s6, s6, 26
	v_sub_u32_e32 v0, v0, v1
	s_add_i32 s6, s4, s6
	v_lshrrev_b32_e32 v1, 4, v0
	s_ashr_i32 s7, s6, 6
	s_and_b32 s6, s6, 0xffc0
	v_bitop3_b32 v0, v1, v0, 32 bitop3:0x6c
	s_sub_i32 s6, s4, s6
	v_ashrrev_i32_e32 v2, 31, v0
	s_bfe_i32 s4, s6, 0x80000
	v_lshrrev_b32_e32 v2, 26, v2
	s_bfe_u32 s4, s4, 0x3000c
	v_lshlrev_b32_e32 v1, 3, v13
	v_add_u32_e32 v2, v0, v2
	s_add_i32 s8, s6, s4
	v_and_b32_e32 v1, -16, v1
	v_ashrrev_i32_e32 v14, 6, v2
	v_lshlrev_b32_e32 v4, 5, v13
	s_bfe_i32 s4, s8, 0x80000
	s_and_b32 s8, s8, 0xf8
	v_add_u32_e32 v1, v14, v1
	v_and_b32_e32 v15, 32, v4
	v_and_b32_e32 v4, 3, v14
	s_sext_i32_i16 s9, s4
	s_sub_i32 s6, s6, s8
	v_and_b32_e32 v2, 0xc0, v2
	v_and_or_b32 v4, v1, s5, v4
	s_ashr_i32 s5, s33, 6
	s_lshl_b32 s7, s7, 3
	s_sext_i32_i8 s6, s6
	s_ashr_i32 s8, s9, 3
	s_ashr_i32 s3, s33, 8
	v_sub_u32_e32 v0, v0, v2
	s_lshl_b32 s40, s5, 10
	s_lshr_b32 s4, s9, 3
	s_add_i32 s63, s7, s6
	s_mul_hi_i32 s9, s8, 0x140000
	s_mul_i32 s8, s8, 0x140000
	v_readlane_b32 s14, v252, 32
	v_ashrrev_i16_sdwa v0, v3, sext(v0) dst_sel:DWORD dst_unused:UNUSED_PAD src0_sel:DWORD src1_sel:BYTE_0
	v_lshlrev_b32_e32 v2, 1, v1
	v_lshrrev_b32_e32 v3, 2, v1
	v_readlane_b32 s15, v252, 33
	s_add_u32 s34, s14, s8
	v_bfe_i32 v16, v0, 0, 16
	v_and_b32_e32 v2, 24, v2
	v_and_b32_e32 v3, 4, v3
	s_addc_u32 s35, s15, s9
	s_add_i32 s41, s40, 0
	v_add_u32_e32 v0, v15, v16
	v_or3_b32 v2, v4, v3, v2
	v_mul_lo_u32 v1, v1, s2
	s_add_i32 m0, s41, 0x10000
	v_add_lshl_u32 v132, v0, v1, 1
	v_mul_u32_u24_e32 v1, 0xa00, v2
	s_mul_i32 s7, s63, 0x140000
	global_load_lds_dwordx4 v130, s[34:35]
	s_add_i32 m0, s41, 0x12000
	v_add_lshl_u32 v134, v1, v0, 1
	s_mul_hi_i32 s6, s63, 0x140000
	s_add_u32 s30, s16, s7
	global_load_lds_dwordx4 v134, s[34:35]
	s_addc_u32 s31, s17, s6
	s_mov_b32 m0, s41
	s_add_i32 s42, s41, 0x2000
	global_load_lds_dwordx4 v128, s[30:31]
	s_mov_b32 m0, s42
	s_add_u32 s6, s34, 0xa0000
	global_load_lds_dwordx4 v132, s[30:31]
	s_addc_u32 s7, s35, 0
	s_add_i32 m0, s41, 0x14000
	v_mov_b32_e32 v131, 0
	global_load_lds_dwordx4 v130, s[6:7]
	s_add_i32 m0, s41, 0x16000
	v_mov_b32_e32 v135, v131
	global_load_lds_dwordx4 v134, s[6:7]
	s_add_u32 s6, s30, 0xa0000
	s_addc_u32 s7, s31, 0
	s_add_i32 s43, s41, 0x4000
	s_mov_b32 m0, s43
	s_add_i32 s44, s41, 0x6000
	global_load_lds_dwordx4 v128, s[6:7]
	s_mov_b32 m0, s44
	v_mov_b32_e32 v129, v131
	global_load_lds_dwordx4 v132, s[6:7]
	v_mov_b32_e32 v133, v131
	s_mov_b32 s45, 0
	s_mov_b32 s48, 0x10000
	v_lshl_add_u64 v[6:7], s[34:35], 0, v[130:131]
	v_lshl_add_u64 v[4:5], s[34:35], 0, v[134:135]
	v_lshl_add_u64 v[2:3], s[30:31], 0, v[128:129]
	v_lshl_add_u64 v[0:1], s[30:31], 0, v[132:133]
	s_cmp_lg_u32 s3, 1
	s_mov_b64 s[8:9], 0xa0000
	s_cbranch_scc1 .LBB0_1390
	s_barrier
	s_setprio 1
